# res_fixup item body rewritten by hand: all 8 partial and 4 X loads in one round trip
# speedup vs baseline: 1.0024x; 1.0024x over previous
; template <class FrameT>
; __device__ __forceinline__ void res_fixup(FrameT& F, const EpiRes& E, const pg8::DpSplit& S) {
;     ...
;         const int j = item >> 3, ai = (item >> 2) & 1, m = item & 3;
;         pg8::Unit u; S.unit_of(S.G + j, u);
;         const int r = u.pm * 256 + wr * 64 + fr + ai * 128 + m * 16, col0 = u.pn * 256 + wc * 32 + 8 * fq;
;         float q = 0.f;
; #pragma unroll
;         for (int bj = 0; bj < 2; ++bj) {
;             f32x4 a0 = {0.f, 0.f, 0.f, 0.f}, a1 = {0.f, 0.f, 0.f, 0.f};
; #pragma unroll
;             for (int p = 0; p < 4; ++p) {
;                 const float* sp = S.slab + (size_t)(4 * j + p) * 65536 + (size_t)(((ai * 2 + bj) * 4 + m) * 2048) + tid * 4;
;                 const u32x4 w = __builtin_nontemporal_load((const u32x4*)sp);
;                 a0 += (f32x4){__uint_as_float(w.x << 16), __uint_as_float(w.x & 0xffff0000u), __uint_as_float(w.y << 16), __uint_as_float(w.y & 0xffff0000u)};
;                 a1 += (f32x4){__uint_as_float(w.z << 16), __uint_as_float(w.z & 0xffff0000u), __uint_as_float(w.w << 16), __uint_as_float(w.w & 0xffff0000u)};
;             }
;             float* xp = E.X + (size_t)r * D + col0 + bj * 128;
;             f32x4 v0 = *(f32x4*)xp, v1 = *(f32x4*)(xp + 4);
.LBB0_506:
	s_add_i32 s2, s9, s2
	s_ashr_i32 s3, s2, 31
	s_lshr_b32 s3, s3, 27
	s_add_i32 s3, s2, s3
	s_ashr_i32 s9, s3, 5
	s_lshl_b32 s9, s9, 3
	s_sub_i32 s20, 0x45, s9
	s_min_i32 s20, s20, 8
	s_abs_i32 s22, s20
	v_cvt_f32_u32_e32 v0, s22
	s_sub_i32 s23, 0, s22
	s_andn2_b32 s3, s3, 31
	s_sub_i32 s2, s2, s3
	v_rcp_iflag_f32_e32 v0, v0
	s_abs_i32 s21, s2
	s_xor_b32 s3, s2, s20
	s_bfe_u32 s18, s17, 0x10002
	v_mul_f32_e32 v0, 0x4f7ffffe, v0
	v_cvt_u32_f32_e32 v0, v0
	s_and_b32 s19, s17, 3
	s_ashr_i32 s3, s3, 31
	v_mov_b32_e32 v175, v174
	v_readfirstlane_b32 s24, v0
	s_mul_i32 s23, s23, s24
	s_mul_hi_u32 s23, s24, s23
	s_add_i32 s24, s24, s23
	s_mul_hi_u32 s23, s21, s24
	s_mul_i32 s24, s23, s22
	s_sub_i32 s21, s21, s24
	s_add_i32 s24, s23, 1
	s_sub_i32 s25, s21, s22
	s_cmp_ge_u32 s21, s22
	s_cselect_b32 s23, s24, s23
	s_cselect_b32 s21, s25, s21
	s_add_i32 s24, s23, 1
	s_cmp_ge_u32 s21, s22
	s_cselect_b32 s21, s24, s23
	s_xor_b32 s21, s21, s3
	s_sub_i32 s3, s21, s3
	s_mul_i32 s20, s3, s20
	s_sub_i32 s2, s2, s20
	s_add_i32 s9, s9, s2
	s_lshl_b32 s2, s9, 8
	s_lshl_b32 s9, s18, 7
	s_lshl_b32 s20, s8, 2
	v_lshl_or_b32 v0, s19, 4, v22
	s_or_b32 s2, s2, s9
	s_ashr_i32 s21, s20, 31
	s_lshl_b32 s8, s19, 13
	s_lshl_b32 s9, s18, 16
	v_add_u32_e32 v8, s2, v0
	v_lshl_or_b32 v2, s3, 8, v23
	s_lshl_b64 s[2:3], s[20:21], 18
	s_or_b32 s8, s9, s8
	s_add_u32 s8, s72, s8
	s_addc_u32 s9, s73, 0
	s_waitcnt lgkmcnt(0)
	v_lshl_add_u64 v[0:1], v[4:5], 2, s[8:9]
	v_lshl_add_u64 v[10:11], v[0:1], 0, s[2:3]
	global_load_dwordx4 v[10:13], v[10:11], off nt
	s_or_b32 s8, s20, 1
	s_ashr_i32 s9, s8, 31
	s_lshl_b64 s[8:9], s[8:9], 18
	s_or_b32 s18, s20, 2
	s_ashr_i32 s19, s18, 31
	s_lshl_b64 s[18:19], s[18:19], 18
	s_or_b32 s20, s20, 3
	s_ashr_i32 s21, s20, 31
	s_lshl_b64 s[20:21], s[20:21], 18
	v_ashrrev_i32_e32 v9, 31, v8
	v_ashrrev_i32_e32 v3, 31, v2
	s_mov_b64 s[22:23], 0x8000
	v_lshl_add_u64 v[32:33], v[0:1], 0, s[8:9]
	global_load_dwordx4 v[36:39], v[32:33], off nt
	v_lshl_add_u64 v[34:35], v[32:33], 0, s[22:23]
	global_load_dwordx4 v[52:55], v[34:35], off nt
	v_lshl_add_u64 v[32:33], v[0:1], 0, s[18:19]
	global_load_dwordx4 v[40:43], v[32:33], off nt
	v_lshl_add_u64 v[34:35], v[32:33], 0, s[22:23]
	global_load_dwordx4 v[56:59], v[34:35], off nt
	v_lshl_add_u64 v[32:33], v[0:1], 0, s[20:21]
	global_load_dwordx4 v[44:47], v[32:33], off nt
	v_lshl_add_u64 v[34:35], v[32:33], 0, s[22:23]
	global_load_dwordx4 v[60:63], v[34:35], off nt
	v_lshl_add_u64 v[32:33], v[0:1], 0, s[2:3]
	v_lshl_add_u64 v[34:35], v[32:33], 0, s[22:23]
	global_load_dwordx4 v[48:51], v[34:35], off nt
	v_lshlrev_b64 v[32:33], 12, v[8:9]
	v_lshl_add_u64 v[32:33], s[10:11], 0, v[32:33]
	v_lshl_add_u64 v[32:33], v[2:3], 2, v[32:33]
	global_load_dwordx4 v[64:67], v[32:33], off
	global_load_dwordx4 v[68:71], v[32:33], off offset:16
	global_load_dwordx4 v[72:75], v[32:33], off offset:512
	global_load_dwordx4 v[76:79], v[32:33], off offset:528
	v_lshlrev_b64 v[34:35], 11, v[8:9]
	v_lshl_add_u64 v[34:35], s[12:13], 0, v[34:35]
	v_lshl_add_u64 v[34:35], v[2:3], 1, v[34:35]
	s_waitcnt vmcnt(0)
; __device__ __forceinline__ unsigned pk2(float lo, float hi) { unsigned r; asm("v_cvt_pk_bf16_f32 %0, %1, %2" : "=v"(r) : "v"(lo), "v"(hi)); return r; }
; template <class FrameT>
; __device__ __forceinline__ void res_fixup(FrameT& F, const EpiRes& E, const pg8::DpSplit& S) {
;     ...
; #pragma unroll
;         for (int bj = 0; bj < 2; ++bj) {
;             f32x4 a0 = {0.f, 0.f, 0.f, 0.f}, a1 = {0.f, 0.f, 0.f, 0.f};
; #pragma unroll
;             for (int p = 0; p < 4; ++p) {
;                 const float* sp = S.slab + (size_t)(4 * j + p) * 65536 + (size_t)(((ai * 2 + bj) * 4 + m) * 2048) + tid * 4;
;                 const u32x4 w = __builtin_nontemporal_load((const u32x4*)sp);
;                 a0 += (f32x4){__uint_as_float(w.x << 16), __uint_as_float(w.x & 0xffff0000u), __uint_as_float(w.y << 16), __uint_as_float(w.y & 0xffff0000u)};
;                 a1 += (f32x4){__uint_as_float(w.z << 16), __uint_as_float(w.z & 0xffff0000u), __uint_as_float(w.w << 16), __uint_as_float(w.w & 0xffff0000u)};
;             }
;             float* xp = E.X + (size_t)r * D + col0 + bj * 128;
;             f32x4 v0 = *(f32x4*)xp, v1 = *(f32x4*)(xp + 4);
;             v0 = v0 + a0 * E.scale; v1 = v1 + a1 * E.scale;
;             *(f32x4*)xp = v0; *(f32x4*)(xp + 4) = v1;
;             u32x4 w; w.x = pk2(v0[0], v0[1]); w.y = pk2(v0[2], v0[3]); w.z = pk2(v1[0], v1[1]); w.w = pk2(v1[2], v1[3]);
;             *(u32x4*)(E.XB + (size_t)r * D + col0 + bj * 128) = w;
;             q += (v0[0] * v0[0] + v0[1] * v0[1]) + (v0[2] * v0[2] + v0[3] * v0[3]) + (v1[0] * v1[0] + v1[1] * v1[1]) + (v1[2] * v1[2] + v1[3] * v1[3]);
;         }
;         q += __shfl_xor(q, 16); q += __shfl_xor(q, 32);
;         if (fq == 0) atomicAdd(E.ssn + r, q);
	v_lshlrev_b32_e32 v80, 16, v10
	v_and_b32_e32 v81, 0xffff0000, v10
	v_pk_add_f32 v[82:83], v[80:81], 0 op_sel_hi:[1,0]
	v_lshlrev_b32_e32 v80, 16, v36
	v_and_b32_e32 v81, 0xffff0000, v36
	v_pk_add_f32 v[82:83], v[82:83], v[80:81]
	v_lshlrev_b32_e32 v80, 16, v40
	v_and_b32_e32 v81, 0xffff0000, v40
	v_pk_add_f32 v[82:83], v[82:83], v[80:81]
	v_lshlrev_b32_e32 v80, 16, v44
	v_and_b32_e32 v81, 0xffff0000, v44
	v_pk_add_f32 v[82:83], v[82:83], v[80:81]
	v_lshlrev_b32_e32 v80, 16, v11
	v_and_b32_e32 v81, 0xffff0000, v11
	v_pk_add_f32 v[84:85], v[80:81], 0 op_sel_hi:[1,0]
	v_lshlrev_b32_e32 v80, 16, v37
	v_and_b32_e32 v81, 0xffff0000, v37
	v_pk_add_f32 v[84:85], v[84:85], v[80:81]
	v_lshlrev_b32_e32 v80, 16, v41
	v_and_b32_e32 v81, 0xffff0000, v41
	v_pk_add_f32 v[84:85], v[84:85], v[80:81]
	v_lshlrev_b32_e32 v80, 16, v45
	v_and_b32_e32 v81, 0xffff0000, v45
	v_pk_add_f32 v[84:85], v[84:85], v[80:81]
	v_lshlrev_b32_e32 v80, 16, v12
	v_and_b32_e32 v81, 0xffff0000, v12
	v_pk_add_f32 v[86:87], v[80:81], 0 op_sel_hi:[1,0]
	v_lshlrev_b32_e32 v80, 16, v38
	v_and_b32_e32 v81, 0xffff0000, v38
	v_pk_add_f32 v[86:87], v[86:87], v[80:81]
	v_lshlrev_b32_e32 v80, 16, v42
	v_and_b32_e32 v81, 0xffff0000, v42
	v_pk_add_f32 v[86:87], v[86:87], v[80:81]
	v_lshlrev_b32_e32 v80, 16, v46
	v_and_b32_e32 v81, 0xffff0000, v46
	v_pk_add_f32 v[86:87], v[86:87], v[80:81]
	v_lshlrev_b32_e32 v80, 16, v13
	v_and_b32_e32 v81, 0xffff0000, v13
	v_pk_add_f32 v[88:89], v[80:81], 0 op_sel_hi:[1,0]
	v_lshlrev_b32_e32 v80, 16, v39
	v_and_b32_e32 v81, 0xffff0000, v39
	v_pk_add_f32 v[88:89], v[88:89], v[80:81]
	v_lshlrev_b32_e32 v80, 16, v43
	v_and_b32_e32 v81, 0xffff0000, v43
	v_pk_add_f32 v[88:89], v[88:89], v[80:81]
	v_lshlrev_b32_e32 v80, 16, v47
	v_and_b32_e32 v81, 0xffff0000, v47
	v_pk_add_f32 v[88:89], v[88:89], v[80:81]
	v_pk_fma_f32 v[64:65], v[6:7], v[82:83], v[64:65]
	v_pk_fma_f32 v[66:67], v[6:7], v[84:85], v[66:67]
	v_pk_fma_f32 v[68:69], v[6:7], v[86:87], v[68:69]
	v_pk_fma_f32 v[70:71], v[6:7], v[88:89], v[70:71]
	global_store_dwordx4 v[32:33], v[64:67], off
	global_store_dwordx4 v[32:33], v[68:71], off offset:16
	v_cvt_pk_bf16_f32 v90, v64, v65
	v_cvt_pk_bf16_f32 v91, v66, v67
	v_cvt_pk_bf16_f32 v92, v68, v69
	v_cvt_pk_bf16_f32 v93, v70, v71
	v_mul_f32_e32 v94, v64, v64
	v_fmac_f32_e32 v94, v65, v65
	v_fmac_f32_e32 v94, v66, v66
	v_fmac_f32_e32 v94, v67, v67
	v_fmac_f32_e32 v94, v68, v68
	v_fmac_f32_e32 v94, v69, v69
	v_fmac_f32_e32 v94, v70, v70
	v_fmac_f32_e32 v94, v71, v71
	global_store_dwordx4 v[34:35], v[90:93], off
	v_lshlrev_b32_e32 v80, 16, v48
	v_and_b32_e32 v81, 0xffff0000, v48
	v_pk_add_f32 v[82:83], v[80:81], 0 op_sel_hi:[1,0]
	v_lshlrev_b32_e32 v80, 16, v52
	v_and_b32_e32 v81, 0xffff0000, v52
	v_pk_add_f32 v[82:83], v[82:83], v[80:81]
	v_lshlrev_b32_e32 v80, 16, v56
	v_and_b32_e32 v81, 0xffff0000, v56
	v_pk_add_f32 v[82:83], v[82:83], v[80:81]
	v_lshlrev_b32_e32 v80, 16, v60
	v_and_b32_e32 v81, 0xffff0000, v60
	v_pk_add_f32 v[82:83], v[82:83], v[80:81]
	v_lshlrev_b32_e32 v80, 16, v49
	v_and_b32_e32 v81, 0xffff0000, v49
	v_pk_add_f32 v[84:85], v[80:81], 0 op_sel_hi:[1,0]
	v_lshlrev_b32_e32 v80, 16, v53
	v_and_b32_e32 v81, 0xffff0000, v53
	v_pk_add_f32 v[84:85], v[84:85], v[80:81]
	v_lshlrev_b32_e32 v80, 16, v57
	v_and_b32_e32 v81, 0xffff0000, v57
	v_pk_add_f32 v[84:85], v[84:85], v[80:81]
	v_lshlrev_b32_e32 v80, 16, v61
	v_and_b32_e32 v81, 0xffff0000, v61
	v_pk_add_f32 v[84:85], v[84:85], v[80:81]
	v_lshlrev_b32_e32 v80, 16, v50
	v_and_b32_e32 v81, 0xffff0000, v50
	v_pk_add_f32 v[86:87], v[80:81], 0 op_sel_hi:[1,0]
	v_lshlrev_b32_e32 v80, 16, v54
	v_and_b32_e32 v81, 0xffff0000, v54
	v_pk_add_f32 v[86:87], v[86:87], v[80:81]
	v_lshlrev_b32_e32 v80, 16, v58
	v_and_b32_e32 v81, 0xffff0000, v58
	v_pk_add_f32 v[86:87], v[86:87], v[80:81]
	v_lshlrev_b32_e32 v80, 16, v62
	v_and_b32_e32 v81, 0xffff0000, v62
	v_pk_add_f32 v[86:87], v[86:87], v[80:81]
	v_lshlrev_b32_e32 v80, 16, v51
	v_and_b32_e32 v81, 0xffff0000, v51
	v_pk_add_f32 v[88:89], v[80:81], 0 op_sel_hi:[1,0]
	v_lshlrev_b32_e32 v80, 16, v55
	v_and_b32_e32 v81, 0xffff0000, v55
	v_pk_add_f32 v[88:89], v[88:89], v[80:81]
	v_lshlrev_b32_e32 v80, 16, v59
	v_and_b32_e32 v81, 0xffff0000, v59
	v_pk_add_f32 v[88:89], v[88:89], v[80:81]
	v_lshlrev_b32_e32 v80, 16, v63
	v_and_b32_e32 v81, 0xffff0000, v63
	v_pk_add_f32 v[88:89], v[88:89], v[80:81]
	v_pk_fma_f32 v[72:73], v[6:7], v[82:83], v[72:73]
	v_pk_fma_f32 v[74:75], v[6:7], v[84:85], v[74:75]
	v_pk_fma_f32 v[76:77], v[6:7], v[86:87], v[76:77]
	v_pk_fma_f32 v[78:79], v[6:7], v[88:89], v[78:79]
	global_store_dwordx4 v[32:33], v[72:75], off offset:512
	global_store_dwordx4 v[32:33], v[76:79], off offset:528
	v_cvt_pk_bf16_f32 v90, v72, v73
	v_cvt_pk_bf16_f32 v91, v74, v75
	v_cvt_pk_bf16_f32 v92, v76, v77
	v_cvt_pk_bf16_f32 v93, v78, v79
	v_mul_f32_e32 v95, v72, v72
	v_fmac_f32_e32 v95, v73, v73
	v_fmac_f32_e32 v95, v74, v74
	v_fmac_f32_e32 v95, v75, v75
	v_fmac_f32_e32 v95, v76, v76
	v_fmac_f32_e32 v95, v77, v77
	v_fmac_f32_e32 v95, v78, v78
	v_fmac_f32_e32 v95, v79, v79
	global_store_dwordx4 v[34:35], v[90:93], off offset:256
	v_add_f32_e32 v0, v94, v95
	v_xor_b32_e32 v1, 16, v196
	v_add_u32_e32 v2, 64, v197
	v_cmp_lt_i32_e32 vcc, v1, v2
	s_nop 1
	v_cndmask_b32_e32 v1, v196, v1, vcc
	v_lshlrev_b32_e32 v1, 2, v1
	ds_bpermute_b32 v1, v1, v0
	s_waitcnt lgkmcnt(0)
	v_add_f32_e32 v0, v0, v1
	v_xor_b32_e32 v1, 32, v196
	v_cmp_lt_i32_e32 vcc, v1, v2
	s_nop 1
	v_cndmask_b32_e32 v1, v196, v1, vcc
	v_lshlrev_b32_e32 v1, 2, v1
	ds_bpermute_b32 v1, v1, v0
	s_and_saveexec_b64 s[2:3], s[6:7]
	s_cbranch_execz .LBB0_501
	v_lshl_add_u64 v[2:3], v[8:9], 2, s[14:15]
	s_waitcnt lgkmcnt(0)
	v_add_f32_e32 v0, v0, v1
	global_atomic_add_f32 v[2:3], v0, off
	s_branch .LBB0_501
